# diff-attn unit prologue: unused norm loads retargeted so Q loads and first LDS-DMA are not held behind vmcnt(2)
# baseline (speedup 1.0000x reference)
.LBB0_280:
	v_readlane_b32 s6, v252, 44
	v_readlane_b32 s7, v252, 45
	s_mov_b32 s22, s6
	s_lshl_b32 s6, s6, 6
	s_ashr_i32 s7, s6, 31
	s_lshl_b64 s[6:7], s[6:7], 2
	s_add_u32 s3, s4, s6
	s_addc_u32 s10, s5, s7
	s_lshl_b32 s6, s28, 2
	s_ashr_i32 s7, s6, 31
	s_lshl_b64 s[6:7], s[6:7], 2
	s_mov_b32 s12, s22
	s_add_u32 s6, s3, s6
	v_writelane_b32 v252, s12, 44
	s_addc_u32 s7, s10, s7
	s_lshl_b32 s3, s29, 7
	s_ashr_i32 s23, s22, 31
	s_lshl_b32 s20, s28, 7
	v_writelane_b32 v252, s13, 45
	global_load_dword v202, v231, s[6:7] sc1
	global_load_dword v202, v231, s[6:7] offset:4 sc1
	global_load_dword v8, v231, s[6:7] offset:128 sc1
	global_load_dword v9, v231, s[6:7] offset:132 sc1
	global_load_dword v202, v231, s[6:7] offset:8 sc1
	global_load_dword v202, v231, s[6:7] offset:12 sc1
	global_load_dword v10, v231, s[6:7] offset:136 sc1
	global_load_dword v11, v231, s[6:7] offset:140 sc1
	s_lshl_b64 s[10:11], s[22:23], 12
	s_or_b32 s6, s3, s47
	s_ashr_i32 s21, s20, 31
	s_lshl_b64 s[12:13], s[22:23], 23
	v_readlane_b32 s7, v252, 10
	s_add_u32 s7, s7, s12
	v_readlane_b32 s22, v252, 11
	s_addc_u32 s25, s22, s13
	s_ashr_i32 s22, s6, 31
	s_add_u32 s30, s10, s6
	s_addc_u32 s31, s11, s22
	v_mov_b32_e32 v1, s31
	v_or_b32_e32 v0, s30, v148
	v_lshlrev_b64 v[0:1], 11, v[0:1]
	v_readlane_b32 s22, v255, 0
	v_lshl_add_u64 v[0:1], s[64:65], 0, v[0:1]
	s_lshl_b64 s[10:11], s[20:21], 1
	v_readlane_b32 s23, v255, 1
	v_lshl_add_u64 v[0:1], v[0:1], 0, s[10:11]
	s_mov_b32 s23, s1
	v_lshl_add_u64 v[0:1], v[0:1], 0, s[22:23]
	v_mov_b32_e32 v155, v231
	v_lshl_add_u64 v[0:1], v[0:1], 0, v[154:155]
	global_load_dwordx4 v[96:99], v[0:1], off
	global_load_dwordx4 v[100:103], v[0:1], off offset:32
	global_load_dwordx4 v[104:107], v[0:1], off offset:64
	global_load_dwordx4 v[108:111], v[0:1], off offset:96
	s_mov_b32 s24, s22
	s_add_u32 s12, s87, s12
	v_readlane_b32 s22, v252, 9
	v_add_u32_e32 v4, s3, v169
	s_addc_u32 s13, s22, s13
	v_ashrrev_i32_e32 v5, 31, v4
	s_add_u32 s22, s12, s10
	v_writelane_b32 v255, s24, 0
	v_or_b32_e32 v2, s3, v168
	v_lshlrev_b64 v[4:5], 11, v[4:5]
	s_addc_u32 s23, s13, s11
	v_writelane_b32 v255, s25, 1
	v_lshlrev_b32_e32 v158, 1, v152
	v_mov_b32_e32 v159, v231
	v_ashrrev_i32_e32 v3, 31, v2
	s_add_u32 s24, s7, s10
	v_lshl_add_u64 v[4:5], s[22:23], 0, v[4:5]
	v_lshlrev_b64 v[2:3], 11, v[2:3]
	s_addc_u32 s25, s25, s11
	v_lshl_add_u64 v[4:5], v[4:5], 0, v[158:159]
	s_or_b32 s38, s3, 64
	v_lshlrev_b32_e32 v230, 1, v150
	v_lshl_add_u64 v[0:1], s[24:25], 0, v[2:3]
	v_readlane_b32 s26, v252, 26
	s_mov_b32 s7, m0
	s_mov_b32 m0, s26
	s_nop 0
	global_load_lds_dwordx4 v[4:5], off
	s_mov_b32 m0, s7
	v_lshl_add_u64 v[2:3], v[4:5], 0, s[96:97]
	v_or_b32_e32 v4, s38, v168
	v_add_u32_e32 v6, s38, v169
	s_lshl_b64 s[10:11], s[56:57], 1
	v_lshl_add_u64 v[0:1], v[0:1], 0, v[230:231]
	v_readlane_b32 s26, v252, 19
	s_mov_b32 s7, m0
	s_mov_b32 m0, s26
	s_nop 0
	global_load_lds_dwordx4 v[2:3], off
	s_mov_b32 m0, s7
	v_ashrrev_i32_e32 v5, 31, v4
	v_ashrrev_i32_e32 v7, 31, v6
	s_lshl_b64 s[12:13], s[74:75], 1
	v_lshl_add_u64 v[2:3], v[0:1], 0, s[10:11]
	v_lshlrev_b64 v[4:5], 11, v[4:5]
	v_lshlrev_b64 v[6:7], 11, v[6:7]
	s_mov_b32 s7, m0
	s_mov_b32 m0, s49
	s_nop 0
	global_load_lds_dwordx4 v[2:3], off
	s_mov_b32 m0, s7
	v_lshl_add_u64 v[0:1], v[0:1], 0, s[12:13]
	v_lshl_add_u64 v[2:3], s[24:25], 0, v[4:5]
	v_lshl_add_u64 v[4:5], s[22:23], 0, v[6:7]
	s_mov_b32 s7, m0
	s_mov_b32 m0, s50
	s_nop 0
	global_load_lds_dwordx4 v[0:1], off
	s_mov_b32 m0, s7
	v_lshl_add_u64 v[0:1], v[2:3], 0, v[230:231]
	v_lshl_add_u64 v[2:3], v[4:5], 0, v[158:159]
	v_readlane_b32 s26, v252, 22
	s_mov_b32 s7, m0
	s_mov_b32 m0, s26
	s_nop 0
	global_load_lds_dwordx4 v[2:3], off
	s_mov_b32 m0, s7
	v_lshl_add_u64 v[2:3], v[2:3], 0, s[96:97]
	v_lshl_add_u64 v[4:5], v[0:1], 0, s[10:11]
	v_readlane_b32 s10, v252, 23
	s_mov_b32 s7, m0
	s_mov_b32 m0, s10
	s_nop 0
	global_load_lds_dwordx4 v[2:3], off
	s_mov_b32 m0, s7
	v_lshl_add_u64 v[0:1], v[0:1], 0, s[12:13]
	s_mov_b32 s7, m0
	s_mov_b32 m0, s51
	s_nop 0
	global_load_lds_dwordx4 v[4:5], off
	s_mov_b32 m0, s7
	v_readlane_b32 s10, v252, 28
	s_mov_b32 s7, m0
	s_mov_b32 m0, s77
	s_nop 0
	global_load_lds_dwordx4 v[0:1], off
	s_mov_b32 m0, s7
	s_waitcnt vmcnt(16)
	v_add_f32_e32 v0, v8, v9
	s_waitcnt vmcnt(4)
	v_add_f32_e32 v2, v10, v11
	v_readfirstlane_b32 s7, v0
	v_readlane_b32 s11, v252, 29
	s_andn2_b64 vcc, exec, s[10:11]
	v_readfirstlane_b32 s39, v2
	s_waitcnt vmcnt(3)
	v_and_b32_e32 v0, 0xffff0000, v96
	v_lshlrev_b32_e32 v1, 16, v96
	v_mul_f32_e32 v0, v0, v0
	v_lshlrev_b32_e32 v3, 16, v97
	v_fmac_f32_e32 v0, v1, v1
	v_and_b32_e32 v4, 0xffff0000, v97
	v_fmac_f32_e32 v0, v3, v3
	v_lshlrev_b32_e32 v5, 16, v98
	v_fmac_f32_e32 v0, v4, v4
	v_and_b32_e32 v6, 0xffff0000, v98
	v_fmac_f32_e32 v0, v5, v5
	v_lshlrev_b32_e32 v7, 16, v99
	v_fmac_f32_e32 v0, v6, v6
	v_and_b32_e32 v8, 0xffff0000, v99
	v_fmac_f32_e32 v0, v7, v7
	v_fmac_f32_e32 v0, v8, v8
	s_waitcnt vmcnt(2)
	v_lshlrev_b32_e32 v1, 16, v100
	v_fmac_f32_e32 v0, v1, v1
	v_and_b32_e32 v1, 0xffff0000, v100
	v_fmac_f32_e32 v0, v1, v1
	v_lshlrev_b32_e32 v1, 16, v101
	v_fmac_f32_e32 v0, v1, v1
	v_and_b32_e32 v1, 0xffff0000, v101
	v_fmac_f32_e32 v0, v1, v1
	v_lshlrev_b32_e32 v1, 16, v102
	v_fmac_f32_e32 v0, v1, v1
	v_and_b32_e32 v1, 0xffff0000, v102
	v_fmac_f32_e32 v0, v1, v1
	v_lshlrev_b32_e32 v1, 16, v103
	v_fmac_f32_e32 v0, v1, v1
	v_and_b32_e32 v1, 0xffff0000, v103
	v_fmac_f32_e32 v0, v1, v1
	s_waitcnt vmcnt(1)
	v_lshlrev_b32_e32 v1, 16, v104
	v_fmac_f32_e32 v0, v1, v1
	v_and_b32_e32 v1, 0xffff0000, v104
	v_fmac_f32_e32 v0, v1, v1
	v_lshlrev_b32_e32 v1, 16, v105
	v_fmac_f32_e32 v0, v1, v1
	v_and_b32_e32 v1, 0xffff0000, v105
	v_fmac_f32_e32 v0, v1, v1
	v_lshlrev_b32_e32 v1, 16, v106
	v_fmac_f32_e32 v0, v1, v1
	v_and_b32_e32 v1, 0xffff0000, v106
	v_fmac_f32_e32 v0, v1, v1
	v_lshlrev_b32_e32 v1, 16, v107
	v_fmac_f32_e32 v0, v1, v1
	v_and_b32_e32 v1, 0xffff0000, v107
	v_fmac_f32_e32 v0, v1, v1
	s_waitcnt vmcnt(0)
	v_lshlrev_b32_e32 v1, 16, v108
	v_fmac_f32_e32 v0, v1, v1
	v_and_b32_e32 v1, 0xffff0000, v108
	v_fmac_f32_e32 v0, v1, v1
	v_lshlrev_b32_e32 v1, 16, v109
	v_fmac_f32_e32 v0, v1, v1
	v_and_b32_e32 v1, 0xffff0000, v109
	v_fmac_f32_e32 v0, v1, v1
	v_lshlrev_b32_e32 v1, 16, v110
	v_fmac_f32_e32 v0, v1, v1
	v_and_b32_e32 v1, 0xffff0000, v110
	v_fmac_f32_e32 v0, v1, v1
	v_lshlrev_b32_e32 v1, 16, v111
	v_fmac_f32_e32 v0, v1, v1
	v_and_b32_e32 v1, 0xffff0000, v111
	v_fmac_f32_e32 v0, v1, v1
	v_mbcnt_lo_u32_b32 v1, -1, 0
	v_mbcnt_hi_u32_b32 v1, -1, v1
	s_nop 0
	v_lshlrev_b32_e32 v1, 2, v1
	v_xor_b32_e32 v1, 0x80, v1
	ds_bpermute_b32 v1, v1, v0
	s_cbranch_vccnz .LBB0_282
	s_setprio 1
